# pool-weight fold: row loads software-pipelined 3 groups ahead (on top of nt policy version)
# speedup vs baseline: 1.0502x; 1.0057x over previous
; #define LAS __attribute__((address_space(3)))
; __global__ void __launch_bounds__(512, 2) hybrid_fwd(Args args) {
;     ...
;             const float* wp = w_pool_out + (size_t)g * 128 * DM + n;
; #pragma unroll 16
;             for (int d = 0; d < 128; ++d) {
;                 const float p = wp[(size_t)d * DM];
;                 const f32x4 a = *(const LAS f32x4*)(scr + d * 4);
;                 acc[0] += a[0] * p; acc[1] += a[1] * p; acc[2] += a[2] * p; acc[3] += a[3] * p;
;             }
.LBB0_49:
	v_add_lshl_u32 v72, s26, v160, 2
	v_mov_b32_e32 v73, s3
	global_load_dword v74, v72, s[24:25]
	s_add_u32 s24, s24, 0x1000
	s_addc_u32 s25, s25, 0
	global_load_dword v75, v72, s[24:25]
	s_add_u32 s24, s24, 0x1000
	s_addc_u32 s25, s25, 0
	global_load_dword v76, v72, s[24:25]
	s_add_u32 s24, s24, 0x1000
	s_addc_u32 s25, s25, 0
	global_load_dword v77, v72, s[24:25]
	s_add_u32 s24, s24, 0x1000
	s_addc_u32 s25, s25, 0
	global_load_dword v78, v72, s[24:25]
	s_add_u32 s24, s24, 0x1000
	s_addc_u32 s25, s25, 0
	global_load_dword v79, v72, s[24:25]
	s_add_u32 s24, s24, 0x1000
	s_addc_u32 s25, s25, 0
	global_load_dword v80, v72, s[24:25]
	s_add_u32 s24, s24, 0x1000
	s_addc_u32 s25, s25, 0
	global_load_dword v81, v72, s[24:25]
	s_add_u32 s24, s24, 0x1000
	s_addc_u32 s25, s25, 0
	global_load_dword v82, v72, s[24:25]
	s_add_u32 s24, s24, 0x1000
	s_addc_u32 s25, s25, 0
	global_load_dword v83, v72, s[24:25]
	s_add_u32 s24, s24, 0x1000
	s_addc_u32 s25, s25, 0
	global_load_dword v84, v72, s[24:25]
	s_add_u32 s24, s24, 0x1000
	s_addc_u32 s25, s25, 0
	global_load_dword v85, v72, s[24:25]
	s_add_u32 s24, s24, 0x1000
	s_addc_u32 s25, s25, 0
	global_load_dword v86, v72, s[24:25]
	s_add_u32 s24, s24, 0x1000
	s_addc_u32 s25, s25, 0
	global_load_dword v87, v72, s[24:25]
	s_add_u32 s24, s24, 0x1000
	s_addc_u32 s25, s25, 0
	global_load_dword v88, v72, s[24:25]
	s_add_u32 s24, s24, 0x1000
	s_addc_u32 s25, s25, 0
	global_load_dword v89, v72, s[24:25]
	s_add_u32 s24, s24, 0x1000
	s_addc_u32 s25, s25, 0
	global_load_dword v90, v72, s[24:25]
	s_add_u32 s24, s24, 0x1000
	s_addc_u32 s25, s25, 0
	global_load_dword v91, v72, s[24:25]
	s_add_u32 s24, s24, 0x1000
	s_addc_u32 s25, s25, 0
	global_load_dword v92, v72, s[24:25]
	s_add_u32 s24, s24, 0x1000
	s_addc_u32 s25, s25, 0
	global_load_dword v93, v72, s[24:25]
	s_add_u32 s24, s24, 0x1000
	s_addc_u32 s25, s25, 0
	global_load_dword v94, v72, s[24:25]
	s_add_u32 s24, s24, 0x1000
	s_addc_u32 s25, s25, 0
	global_load_dword v95, v72, s[24:25]
	s_add_u32 s24, s24, 0x1000
	s_addc_u32 s25, s25, 0
	global_load_dword v96, v72, s[24:25]
	s_add_u32 s24, s24, 0x1000
	s_addc_u32 s25, s25, 0
	global_load_dword v97, v72, s[24:25]
	s_add_u32 s24, s24, 0x1000
	s_addc_u32 s25, s25, 0
	global_load_dword v98, v72, s[24:25]
	s_add_u32 s24, s24, 0x1000
	s_addc_u32 s25, s25, 0
	global_load_dword v99, v72, s[24:25]
	s_add_u32 s24, s24, 0x1000
	s_addc_u32 s25, s25, 0
	global_load_dword v100, v72, s[24:25]
	s_add_u32 s24, s24, 0x1000
	s_addc_u32 s25, s25, 0
	global_load_dword v101, v72, s[24:25]
	s_add_u32 s24, s24, 0x1000
	s_addc_u32 s25, s25, 0
	global_load_dword v102, v72, s[24:25]
	s_add_u32 s24, s24, 0x1000
	s_addc_u32 s25, s25, 0
	global_load_dword v103, v72, s[24:25]
	s_add_u32 s24, s24, 0x1000
	s_addc_u32 s25, s25, 0
	global_load_dword v104, v72, s[24:25]
	s_add_u32 s24, s24, 0x1000
	s_addc_u32 s25, s25, 0
	global_load_dword v105, v72, s[24:25]
	s_add_u32 s24, s24, 0x1000
	s_addc_u32 s25, s25, 0
	global_load_dword v106, v72, s[24:25]
	s_add_u32 s24, s24, 0x1000
	s_addc_u32 s25, s25, 0
	global_load_dword v107, v72, s[24:25]
	s_add_u32 s24, s24, 0x1000
	s_addc_u32 s25, s25, 0
	global_load_dword v108, v72, s[24:25]
	s_add_u32 s24, s24, 0x1000
	s_addc_u32 s25, s25, 0
	global_load_dword v109, v72, s[24:25]
	s_add_u32 s24, s24, 0x1000
	s_addc_u32 s25, s25, 0
	global_load_dword v110, v72, s[24:25]
	s_add_u32 s24, s24, 0x1000
	s_addc_u32 s25, s25, 0
	global_load_dword v111, v72, s[24:25]
	s_add_u32 s24, s24, 0x1000
	s_addc_u32 s25, s25, 0
	global_load_dword v112, v72, s[24:25]
	s_add_u32 s24, s24, 0x1000
	s_addc_u32 s25, s25, 0
	global_load_dword v113, v72, s[24:25]
	s_add_u32 s24, s24, 0x1000
	s_addc_u32 s25, s25, 0
	global_load_dword v114, v72, s[24:25]
	s_add_u32 s24, s24, 0x1000
	s_addc_u32 s25, s25, 0
	global_load_dword v115, v72, s[24:25]
	s_add_u32 s24, s24, 0x1000
	s_addc_u32 s25, s25, 0
	global_load_dword v116, v72, s[24:25]
	s_add_u32 s24, s24, 0x1000
	s_addc_u32 s25, s25, 0
	global_load_dword v117, v72, s[24:25]
	s_add_u32 s24, s24, 0x1000
	s_addc_u32 s25, s25, 0
	global_load_dword v118, v72, s[24:25]
	s_add_u32 s24, s24, 0x1000
	s_addc_u32 s25, s25, 0
	global_load_dword v119, v72, s[24:25]
	s_add_u32 s24, s24, 0x1000
	s_addc_u32 s25, s25, 0
	global_load_dword v120, v72, s[24:25]
	s_add_u32 s24, s24, 0x1000
	s_addc_u32 s25, s25, 0
	global_load_dword v121, v72, s[24:25]
	s_add_u32 s24, s24, 0x1000
	s_addc_u32 s25, s25, 0
	ds_read_b128 v[8:11], v73 offset:0
	ds_read_b128 v[12:15], v73 offset:16
	ds_read_b128 v[16:19], v73 offset:32
	ds_read_b128 v[20:23], v73 offset:48
	ds_read_b128 v[24:27], v73 offset:64
	ds_read_b128 v[28:31], v73 offset:80
	ds_read_b128 v[32:35], v73 offset:96
	ds_read_b128 v[36:39], v73 offset:112
	ds_read_b128 v[40:43], v73 offset:128
	ds_read_b128 v[44:47], v73 offset:144
	ds_read_b128 v[48:51], v73 offset:160
	ds_read_b128 v[52:55], v73 offset:176
	ds_read_b128 v[56:59], v73 offset:192
	ds_read_b128 v[60:63], v73 offset:208
	ds_read_b128 v[64:67], v73 offset:224
	ds_read_b128 v[68:71], v73 offset:240
	s_waitcnt vmcnt(32)
; #define LAS __attribute__((address_space(3)))
; __global__ void __launch_bounds__(512, 2) hybrid_fwd(Args args) {
;     ...
;             const float* wp = w_pool_out + (size_t)g * 128 * DM + n;
; #pragma unroll 16
;             for (int d = 0; d < 128; ++d) {
;                 const float p = wp[(size_t)d * DM];
;                 const f32x4 a = *(const LAS f32x4*)(scr + d * 4);
;                 acc[0] += a[0] * p; acc[1] += a[1] * p; acc[2] += a[2] * p; acc[3] += a[3] * p;
;             }
	global_load_dword v122, v72, s[24:25]
	s_add_u32 s24, s24, 0x1000
	s_addc_u32 s25, s25, 0
	global_load_dword v123, v72, s[24:25]
	s_add_u32 s24, s24, 0x1000
	s_addc_u32 s25, s25, 0
	global_load_dword v124, v72, s[24:25]
	s_add_u32 s24, s24, 0x1000
	s_addc_u32 s25, s25, 0
	global_load_dword v125, v72, s[24:25]
	s_add_u32 s24, s24, 0x1000
	s_addc_u32 s25, s25, 0
	global_load_dword v126, v72, s[24:25]
	s_add_u32 s24, s24, 0x1000
	s_addc_u32 s25, s25, 0
	global_load_dword v127, v72, s[24:25]
	s_add_u32 s24, s24, 0x1000
	s_addc_u32 s25, s25, 0
	global_load_dword v128, v72, s[24:25]
	s_add_u32 s24, s24, 0x1000
	s_addc_u32 s25, s25, 0
	global_load_dword v129, v72, s[24:25]
	s_add_u32 s24, s24, 0x1000
	s_addc_u32 s25, s25, 0
	global_load_dword v130, v72, s[24:25]
	s_add_u32 s24, s24, 0x1000
	s_addc_u32 s25, s25, 0
	global_load_dword v131, v72, s[24:25]
	s_add_u32 s24, s24, 0x1000
	s_addc_u32 s25, s25, 0
	global_load_dword v132, v72, s[24:25]
	s_add_u32 s24, s24, 0x1000
	s_addc_u32 s25, s25, 0
	global_load_dword v133, v72, s[24:25]
	s_add_u32 s24, s24, 0x1000
	s_addc_u32 s25, s25, 0
	global_load_dword v134, v72, s[24:25]
	s_add_u32 s24, s24, 0x1000
	s_addc_u32 s25, s25, 0
	global_load_dword v135, v72, s[24:25]
	s_add_u32 s24, s24, 0x1000
	s_addc_u32 s25, s25, 0
	global_load_dword v136, v72, s[24:25]
	s_add_u32 s24, s24, 0x1000
	s_addc_u32 s25, s25, 0
	global_load_dword v137, v72, s[24:25]
	s_add_u32 s24, s24, 0x1000
	s_addc_u32 s25, s25, 0
	s_waitcnt lgkmcnt(15)
	v_pk_fma_f32 v[2:3], v[74:75], v[8:9], v[2:3] op_sel_hi:[0,1,1]
	v_pk_fma_f32 v[4:5], v[74:75], v[10:11], v[4:5] op_sel_hi:[0,1,1]
	s_waitcnt lgkmcnt(14)
	v_pk_fma_f32 v[2:3], v[74:75], v[12:13], v[2:3] op_sel:[1,0,0] op_sel_hi:[1,1,1]
	v_pk_fma_f32 v[4:5], v[74:75], v[14:15], v[4:5] op_sel:[1,0,0] op_sel_hi:[1,1,1]
	s_waitcnt lgkmcnt(13)
	v_pk_fma_f32 v[2:3], v[76:77], v[16:17], v[2:3] op_sel_hi:[0,1,1]
	v_pk_fma_f32 v[4:5], v[76:77], v[18:19], v[4:5] op_sel_hi:[0,1,1]
	s_waitcnt lgkmcnt(12)
	v_pk_fma_f32 v[2:3], v[76:77], v[20:21], v[2:3] op_sel:[1,0,0] op_sel_hi:[1,1,1]
	v_pk_fma_f32 v[4:5], v[76:77], v[22:23], v[4:5] op_sel:[1,0,0] op_sel_hi:[1,1,1]
	s_waitcnt lgkmcnt(11)
	v_pk_fma_f32 v[2:3], v[78:79], v[24:25], v[2:3] op_sel_hi:[0,1,1]
	v_pk_fma_f32 v[4:5], v[78:79], v[26:27], v[4:5] op_sel_hi:[0,1,1]
	s_waitcnt lgkmcnt(10)
	v_pk_fma_f32 v[2:3], v[78:79], v[28:29], v[2:3] op_sel:[1,0,0] op_sel_hi:[1,1,1]
	v_pk_fma_f32 v[4:5], v[78:79], v[30:31], v[4:5] op_sel:[1,0,0] op_sel_hi:[1,1,1]
	s_waitcnt lgkmcnt(9)
	v_pk_fma_f32 v[2:3], v[80:81], v[32:33], v[2:3] op_sel_hi:[0,1,1]
	v_pk_fma_f32 v[4:5], v[80:81], v[34:35], v[4:5] op_sel_hi:[0,1,1]
	s_waitcnt lgkmcnt(8)
	v_pk_fma_f32 v[2:3], v[80:81], v[36:37], v[2:3] op_sel:[1,0,0] op_sel_hi:[1,1,1]
	v_pk_fma_f32 v[4:5], v[80:81], v[38:39], v[4:5] op_sel:[1,0,0] op_sel_hi:[1,1,1]
	s_waitcnt lgkmcnt(7)
	v_pk_fma_f32 v[2:3], v[82:83], v[40:41], v[2:3] op_sel_hi:[0,1,1]
	v_pk_fma_f32 v[4:5], v[82:83], v[42:43], v[4:5] op_sel_hi:[0,1,1]
	s_waitcnt lgkmcnt(6)
	v_pk_fma_f32 v[2:3], v[82:83], v[44:45], v[2:3] op_sel:[1,0,0] op_sel_hi:[1,1,1]
	v_pk_fma_f32 v[4:5], v[82:83], v[46:47], v[4:5] op_sel:[1,0,0] op_sel_hi:[1,1,1]
	s_waitcnt lgkmcnt(5)
	v_pk_fma_f32 v[2:3], v[84:85], v[48:49], v[2:3] op_sel_hi:[0,1,1]
	v_pk_fma_f32 v[4:5], v[84:85], v[50:51], v[4:5] op_sel_hi:[0,1,1]
	s_waitcnt lgkmcnt(4)
	v_pk_fma_f32 v[2:3], v[84:85], v[52:53], v[2:3] op_sel:[1,0,0] op_sel_hi:[1,1,1]
	v_pk_fma_f32 v[4:5], v[84:85], v[54:55], v[4:5] op_sel:[1,0,0] op_sel_hi:[1,1,1]
	s_waitcnt lgkmcnt(3)
	v_pk_fma_f32 v[2:3], v[86:87], v[56:57], v[2:3] op_sel_hi:[0,1,1]
	v_pk_fma_f32 v[4:5], v[86:87], v[58:59], v[4:5] op_sel_hi:[0,1,1]
	s_waitcnt lgkmcnt(2)
	v_pk_fma_f32 v[2:3], v[86:87], v[60:61], v[2:3] op_sel:[1,0,0] op_sel_hi:[1,1,1]
	v_pk_fma_f32 v[4:5], v[86:87], v[62:63], v[4:5] op_sel:[1,0,0] op_sel_hi:[1,1,1]
	s_waitcnt lgkmcnt(1)
	v_pk_fma_f32 v[2:3], v[88:89], v[64:65], v[2:3] op_sel_hi:[0,1,1]
	v_pk_fma_f32 v[4:5], v[88:89], v[66:67], v[4:5] op_sel_hi:[0,1,1]
	s_waitcnt lgkmcnt(0)
	v_pk_fma_f32 v[2:3], v[88:89], v[68:69], v[2:3] op_sel:[1,0,0] op_sel_hi:[1,1,1]
	v_pk_fma_f32 v[4:5], v[88:89], v[70:71], v[4:5] op_sel:[1,0,0] op_sel_hi:[1,1,1]
	ds_read_b128 v[8:11], v73 offset:256
	ds_read_b128 v[12:15], v73 offset:272
	ds_read_b128 v[16:19], v73 offset:288
	ds_read_b128 v[20:23], v73 offset:304
	ds_read_b128 v[24:27], v73 offset:320
	ds_read_b128 v[28:31], v73 offset:336
	ds_read_b128 v[32:35], v73 offset:352
	ds_read_b128 v[36:39], v73 offset:368
	ds_read_b128 v[40:43], v73 offset:384
	ds_read_b128 v[44:47], v73 offset:400
	ds_read_b128 v[48:51], v73 offset:416
	ds_read_b128 v[52:55], v73 offset:432
	ds_read_b128 v[56:59], v73 offset:448
	ds_read_b128 v[60:63], v73 offset:464
	ds_read_b128 v[64:67], v73 offset:480
	ds_read_b128 v[68:71], v73 offset:496
	s_waitcnt vmcnt(32)
	global_load_dword v74, v72, s[24:25]
	s_add_u32 s24, s24, 0x1000
	s_addc_u32 s25, s25, 0
	global_load_dword v75, v72, s[24:25]
	s_add_u32 s24, s24, 0x1000
	s_addc_u32 s25, s25, 0
	global_load_dword v76, v72, s[24:25]
	s_add_u32 s24, s24, 0x1000
	s_addc_u32 s25, s25, 0
	global_load_dword v77, v72, s[24:25]
	s_add_u32 s24, s24, 0x1000
	s_addc_u32 s25, s25, 0
	global_load_dword v78, v72, s[24:25]
	s_add_u32 s24, s24, 0x1000
	s_addc_u32 s25, s25, 0
	global_load_dword v79, v72, s[24:25]
	s_add_u32 s24, s24, 0x1000
	s_addc_u32 s25, s25, 0
	global_load_dword v80, v72, s[24:25]
	s_add_u32 s24, s24, 0x1000
	s_addc_u32 s25, s25, 0
	global_load_dword v81, v72, s[24:25]
	s_add_u32 s24, s24, 0x1000
	s_addc_u32 s25, s25, 0
	global_load_dword v82, v72, s[24:25]
	s_add_u32 s24, s24, 0x1000
	s_addc_u32 s25, s25, 0
	global_load_dword v83, v72, s[24:25]
	s_add_u32 s24, s24, 0x1000
	s_addc_u32 s25, s25, 0
	global_load_dword v84, v72, s[24:25]
	s_add_u32 s24, s24, 0x1000
	s_addc_u32 s25, s25, 0
	global_load_dword v85, v72, s[24:25]
	s_add_u32 s24, s24, 0x1000
	s_addc_u32 s25, s25, 0
	global_load_dword v86, v72, s[24:25]
	s_add_u32 s24, s24, 0x1000
	s_addc_u32 s25, s25, 0
	global_load_dword v87, v72, s[24:25]
	s_add_u32 s24, s24, 0x1000
	s_addc_u32 s25, s25, 0
	global_load_dword v88, v72, s[24:25]
	s_add_u32 s24, s24, 0x1000
	s_addc_u32 s25, s25, 0
	global_load_dword v89, v72, s[24:25]
	s_add_u32 s24, s24, 0x1000
	s_addc_u32 s25, s25, 0
	s_waitcnt lgkmcnt(15)
; #define LAS __attribute__((address_space(3)))
; __global__ void __launch_bounds__(512, 2) hybrid_fwd(Args args) {
;     ...
;             const float* wp = w_pool_out + (size_t)g * 128 * DM + n;
; #pragma unroll 16
;             for (int d = 0; d < 128; ++d) {
;                 const float p = wp[(size_t)d * DM];
;                 const f32x4 a = *(const LAS f32x4*)(scr + d * 4);
;                 acc[0] += a[0] * p; acc[1] += a[1] * p; acc[2] += a[2] * p; acc[3] += a[3] * p;
;             }
	v_pk_fma_f32 v[2:3], v[90:91], v[8:9], v[2:3] op_sel_hi:[0,1,1]
	v_pk_fma_f32 v[4:5], v[90:91], v[10:11], v[4:5] op_sel_hi:[0,1,1]
	s_waitcnt lgkmcnt(14)
	v_pk_fma_f32 v[2:3], v[90:91], v[12:13], v[2:3] op_sel:[1,0,0] op_sel_hi:[1,1,1]
	v_pk_fma_f32 v[4:5], v[90:91], v[14:15], v[4:5] op_sel:[1,0,0] op_sel_hi:[1,1,1]
	s_waitcnt lgkmcnt(13)
	v_pk_fma_f32 v[2:3], v[92:93], v[16:17], v[2:3] op_sel_hi:[0,1,1]
	v_pk_fma_f32 v[4:5], v[92:93], v[18:19], v[4:5] op_sel_hi:[0,1,1]
	s_waitcnt lgkmcnt(12)
	v_pk_fma_f32 v[2:3], v[92:93], v[20:21], v[2:3] op_sel:[1,0,0] op_sel_hi:[1,1,1]
	v_pk_fma_f32 v[4:5], v[92:93], v[22:23], v[4:5] op_sel:[1,0,0] op_sel_hi:[1,1,1]
	s_waitcnt lgkmcnt(11)
	v_pk_fma_f32 v[2:3], v[94:95], v[24:25], v[2:3] op_sel_hi:[0,1,1]
	v_pk_fma_f32 v[4:5], v[94:95], v[26:27], v[4:5] op_sel_hi:[0,1,1]
	s_waitcnt lgkmcnt(10)
	v_pk_fma_f32 v[2:3], v[94:95], v[28:29], v[2:3] op_sel:[1,0,0] op_sel_hi:[1,1,1]
	v_pk_fma_f32 v[4:5], v[94:95], v[30:31], v[4:5] op_sel:[1,0,0] op_sel_hi:[1,1,1]
	s_waitcnt lgkmcnt(9)
	v_pk_fma_f32 v[2:3], v[96:97], v[32:33], v[2:3] op_sel_hi:[0,1,1]
	v_pk_fma_f32 v[4:5], v[96:97], v[34:35], v[4:5] op_sel_hi:[0,1,1]
	s_waitcnt lgkmcnt(8)
	v_pk_fma_f32 v[2:3], v[96:97], v[36:37], v[2:3] op_sel:[1,0,0] op_sel_hi:[1,1,1]
	v_pk_fma_f32 v[4:5], v[96:97], v[38:39], v[4:5] op_sel:[1,0,0] op_sel_hi:[1,1,1]
	s_waitcnt lgkmcnt(7)
	v_pk_fma_f32 v[2:3], v[98:99], v[40:41], v[2:3] op_sel_hi:[0,1,1]
	v_pk_fma_f32 v[4:5], v[98:99], v[42:43], v[4:5] op_sel_hi:[0,1,1]
	s_waitcnt lgkmcnt(6)
	v_pk_fma_f32 v[2:3], v[98:99], v[44:45], v[2:3] op_sel:[1,0,0] op_sel_hi:[1,1,1]
	v_pk_fma_f32 v[4:5], v[98:99], v[46:47], v[4:5] op_sel:[1,0,0] op_sel_hi:[1,1,1]
	s_waitcnt lgkmcnt(5)
	v_pk_fma_f32 v[2:3], v[100:101], v[48:49], v[2:3] op_sel_hi:[0,1,1]
	v_pk_fma_f32 v[4:5], v[100:101], v[50:51], v[4:5] op_sel_hi:[0,1,1]
	s_waitcnt lgkmcnt(4)
	v_pk_fma_f32 v[2:3], v[100:101], v[52:53], v[2:3] op_sel:[1,0,0] op_sel_hi:[1,1,1]
	v_pk_fma_f32 v[4:5], v[100:101], v[54:55], v[4:5] op_sel:[1,0,0] op_sel_hi:[1,1,1]
	s_waitcnt lgkmcnt(3)
	v_pk_fma_f32 v[2:3], v[102:103], v[56:57], v[2:3] op_sel_hi:[0,1,1]
	v_pk_fma_f32 v[4:5], v[102:103], v[58:59], v[4:5] op_sel_hi:[0,1,1]
	s_waitcnt lgkmcnt(2)
	v_pk_fma_f32 v[2:3], v[102:103], v[60:61], v[2:3] op_sel:[1,0,0] op_sel_hi:[1,1,1]
	v_pk_fma_f32 v[4:5], v[102:103], v[62:63], v[4:5] op_sel:[1,0,0] op_sel_hi:[1,1,1]
	s_waitcnt lgkmcnt(1)
	v_pk_fma_f32 v[2:3], v[104:105], v[64:65], v[2:3] op_sel_hi:[0,1,1]
	v_pk_fma_f32 v[4:5], v[104:105], v[66:67], v[4:5] op_sel_hi:[0,1,1]
	s_waitcnt lgkmcnt(0)
	v_pk_fma_f32 v[2:3], v[104:105], v[68:69], v[2:3] op_sel:[1,0,0] op_sel_hi:[1,1,1]
	v_pk_fma_f32 v[4:5], v[104:105], v[70:71], v[4:5] op_sel:[1,0,0] op_sel_hi:[1,1,1]
	ds_read_b128 v[8:11], v73 offset:512
	ds_read_b128 v[12:15], v73 offset:528
	ds_read_b128 v[16:19], v73 offset:544
	ds_read_b128 v[20:23], v73 offset:560
	ds_read_b128 v[24:27], v73 offset:576
	ds_read_b128 v[28:31], v73 offset:592
	ds_read_b128 v[32:35], v73 offset:608
	ds_read_b128 v[36:39], v73 offset:624
	ds_read_b128 v[40:43], v73 offset:640
	ds_read_b128 v[44:47], v73 offset:656
	ds_read_b128 v[48:51], v73 offset:672
	ds_read_b128 v[52:55], v73 offset:688
	ds_read_b128 v[56:59], v73 offset:704
	ds_read_b128 v[60:63], v73 offset:720
	ds_read_b128 v[64:67], v73 offset:736
	ds_read_b128 v[68:71], v73 offset:752
	s_waitcnt vmcnt(32)
	global_load_dword v90, v72, s[24:25]
	s_add_u32 s24, s24, 0x1000
	s_addc_u32 s25, s25, 0
	global_load_dword v91, v72, s[24:25]
	s_add_u32 s24, s24, 0x1000
	s_addc_u32 s25, s25, 0
	global_load_dword v92, v72, s[24:25]
	s_add_u32 s24, s24, 0x1000
	s_addc_u32 s25, s25, 0
	global_load_dword v93, v72, s[24:25]
	s_add_u32 s24, s24, 0x1000
	s_addc_u32 s25, s25, 0
	global_load_dword v94, v72, s[24:25]
	s_add_u32 s24, s24, 0x1000
	s_addc_u32 s25, s25, 0
	global_load_dword v95, v72, s[24:25]
	s_add_u32 s24, s24, 0x1000
	s_addc_u32 s25, s25, 0
	global_load_dword v96, v72, s[24:25]
	s_add_u32 s24, s24, 0x1000
	s_addc_u32 s25, s25, 0
	global_load_dword v97, v72, s[24:25]
	s_add_u32 s24, s24, 0x1000
	s_addc_u32 s25, s25, 0
	global_load_dword v98, v72, s[24:25]
	s_add_u32 s24, s24, 0x1000
	s_addc_u32 s25, s25, 0
	global_load_dword v99, v72, s[24:25]
	s_add_u32 s24, s24, 0x1000
	s_addc_u32 s25, s25, 0
	global_load_dword v100, v72, s[24:25]
	s_add_u32 s24, s24, 0x1000
	s_addc_u32 s25, s25, 0
	global_load_dword v101, v72, s[24:25]
	s_add_u32 s24, s24, 0x1000
	s_addc_u32 s25, s25, 0
	global_load_dword v102, v72, s[24:25]
	s_add_u32 s24, s24, 0x1000
	s_addc_u32 s25, s25, 0
	global_load_dword v103, v72, s[24:25]
	s_add_u32 s24, s24, 0x1000
	s_addc_u32 s25, s25, 0
	global_load_dword v104, v72, s[24:25]
	s_add_u32 s24, s24, 0x1000
	s_addc_u32 s25, s25, 0
	global_load_dword v105, v72, s[24:25]
	s_add_u32 s24, s24, 0x1000
	s_addc_u32 s25, s25, 0
	s_waitcnt lgkmcnt(15)
	v_pk_fma_f32 v[2:3], v[106:107], v[8:9], v[2:3] op_sel_hi:[0,1,1]
	v_pk_fma_f32 v[4:5], v[106:107], v[10:11], v[4:5] op_sel_hi:[0,1,1]
	s_waitcnt lgkmcnt(14)
	v_pk_fma_f32 v[2:3], v[106:107], v[12:13], v[2:3] op_sel:[1,0,0] op_sel_hi:[1,1,1]
	v_pk_fma_f32 v[4:5], v[106:107], v[14:15], v[4:5] op_sel:[1,0,0] op_sel_hi:[1,1,1]
	s_waitcnt lgkmcnt(13)
	v_pk_fma_f32 v[2:3], v[108:109], v[16:17], v[2:3] op_sel_hi:[0,1,1]
	v_pk_fma_f32 v[4:5], v[108:109], v[18:19], v[4:5] op_sel_hi:[0,1,1]
	s_waitcnt lgkmcnt(12)
	v_pk_fma_f32 v[2:3], v[108:109], v[20:21], v[2:3] op_sel:[1,0,0] op_sel_hi:[1,1,1]
	v_pk_fma_f32 v[4:5], v[108:109], v[22:23], v[4:5] op_sel:[1,0,0] op_sel_hi:[1,1,1]
	s_waitcnt lgkmcnt(11)
	v_pk_fma_f32 v[2:3], v[110:111], v[24:25], v[2:3] op_sel_hi:[0,1,1]
	v_pk_fma_f32 v[4:5], v[110:111], v[26:27], v[4:5] op_sel_hi:[0,1,1]
	s_waitcnt lgkmcnt(10)
; #define LAS __attribute__((address_space(3)))
; __global__ void __launch_bounds__(512, 2) hybrid_fwd(Args args) {
;     ...
;             const float* wp = w_pool_out + (size_t)g * 128 * DM + n;
; #pragma unroll 16
;             for (int d = 0; d < 128; ++d) {
;                 const float p = wp[(size_t)d * DM];
;                 const f32x4 a = *(const LAS f32x4*)(scr + d * 4);
;                 acc[0] += a[0] * p; acc[1] += a[1] * p; acc[2] += a[2] * p; acc[3] += a[3] * p;
;             }
	v_pk_fma_f32 v[2:3], v[110:111], v[28:29], v[2:3] op_sel:[1,0,0] op_sel_hi:[1,1,1]
	v_pk_fma_f32 v[4:5], v[110:111], v[30:31], v[4:5] op_sel:[1,0,0] op_sel_hi:[1,1,1]
	s_waitcnt lgkmcnt(9)
	v_pk_fma_f32 v[2:3], v[112:113], v[32:33], v[2:3] op_sel_hi:[0,1,1]
	v_pk_fma_f32 v[4:5], v[112:113], v[34:35], v[4:5] op_sel_hi:[0,1,1]
	s_waitcnt lgkmcnt(8)
	v_pk_fma_f32 v[2:3], v[112:113], v[36:37], v[2:3] op_sel:[1,0,0] op_sel_hi:[1,1,1]
	v_pk_fma_f32 v[4:5], v[112:113], v[38:39], v[4:5] op_sel:[1,0,0] op_sel_hi:[1,1,1]
	s_waitcnt lgkmcnt(7)
	v_pk_fma_f32 v[2:3], v[114:115], v[40:41], v[2:3] op_sel_hi:[0,1,1]
	v_pk_fma_f32 v[4:5], v[114:115], v[42:43], v[4:5] op_sel_hi:[0,1,1]
	s_waitcnt lgkmcnt(6)
	v_pk_fma_f32 v[2:3], v[114:115], v[44:45], v[2:3] op_sel:[1,0,0] op_sel_hi:[1,1,1]
	v_pk_fma_f32 v[4:5], v[114:115], v[46:47], v[4:5] op_sel:[1,0,0] op_sel_hi:[1,1,1]
	s_waitcnt lgkmcnt(5)
	v_pk_fma_f32 v[2:3], v[116:117], v[48:49], v[2:3] op_sel_hi:[0,1,1]
	v_pk_fma_f32 v[4:5], v[116:117], v[50:51], v[4:5] op_sel_hi:[0,1,1]
	s_waitcnt lgkmcnt(4)
	v_pk_fma_f32 v[2:3], v[116:117], v[52:53], v[2:3] op_sel:[1,0,0] op_sel_hi:[1,1,1]
	v_pk_fma_f32 v[4:5], v[116:117], v[54:55], v[4:5] op_sel:[1,0,0] op_sel_hi:[1,1,1]
	s_waitcnt lgkmcnt(3)
	v_pk_fma_f32 v[2:3], v[118:119], v[56:57], v[2:3] op_sel_hi:[0,1,1]
	v_pk_fma_f32 v[4:5], v[118:119], v[58:59], v[4:5] op_sel_hi:[0,1,1]
	s_waitcnt lgkmcnt(2)
	v_pk_fma_f32 v[2:3], v[118:119], v[60:61], v[2:3] op_sel:[1,0,0] op_sel_hi:[1,1,1]
	v_pk_fma_f32 v[4:5], v[118:119], v[62:63], v[4:5] op_sel:[1,0,0] op_sel_hi:[1,1,1]
	s_waitcnt lgkmcnt(1)
	v_pk_fma_f32 v[2:3], v[120:121], v[64:65], v[2:3] op_sel_hi:[0,1,1]
	v_pk_fma_f32 v[4:5], v[120:121], v[66:67], v[4:5] op_sel_hi:[0,1,1]
	s_waitcnt lgkmcnt(0)
	v_pk_fma_f32 v[2:3], v[120:121], v[68:69], v[2:3] op_sel:[1,0,0] op_sel_hi:[1,1,1]
	v_pk_fma_f32 v[4:5], v[120:121], v[70:71], v[4:5] op_sel:[1,0,0] op_sel_hi:[1,1,1]
	ds_read_b128 v[8:11], v73 offset:768
	ds_read_b128 v[12:15], v73 offset:784
	ds_read_b128 v[16:19], v73 offset:800
	ds_read_b128 v[20:23], v73 offset:816
	ds_read_b128 v[24:27], v73 offset:832
	ds_read_b128 v[28:31], v73 offset:848
	ds_read_b128 v[32:35], v73 offset:864
	ds_read_b128 v[36:39], v73 offset:880
	ds_read_b128 v[40:43], v73 offset:896
	ds_read_b128 v[44:47], v73 offset:912
	ds_read_b128 v[48:51], v73 offset:928
	ds_read_b128 v[52:55], v73 offset:944
	ds_read_b128 v[56:59], v73 offset:960
	ds_read_b128 v[60:63], v73 offset:976
	ds_read_b128 v[64:67], v73 offset:992
	ds_read_b128 v[68:71], v73 offset:1008
	s_waitcnt vmcnt(32)
	global_load_dword v106, v72, s[24:25]
	s_add_u32 s24, s24, 0x1000
	s_addc_u32 s25, s25, 0
	global_load_dword v107, v72, s[24:25]
	s_add_u32 s24, s24, 0x1000
	s_addc_u32 s25, s25, 0
	global_load_dword v108, v72, s[24:25]
	s_add_u32 s24, s24, 0x1000
	s_addc_u32 s25, s25, 0
	global_load_dword v109, v72, s[24:25]
	s_add_u32 s24, s24, 0x1000
	s_addc_u32 s25, s25, 0
	global_load_dword v110, v72, s[24:25]
	s_add_u32 s24, s24, 0x1000
	s_addc_u32 s25, s25, 0
	global_load_dword v111, v72, s[24:25]
	s_add_u32 s24, s24, 0x1000
	s_addc_u32 s25, s25, 0
	global_load_dword v112, v72, s[24:25]
	s_add_u32 s24, s24, 0x1000
	s_addc_u32 s25, s25, 0
	global_load_dword v113, v72, s[24:25]
	s_add_u32 s24, s24, 0x1000
	s_addc_u32 s25, s25, 0
	global_load_dword v114, v72, s[24:25]
	s_add_u32 s24, s24, 0x1000
	s_addc_u32 s25, s25, 0
	global_load_dword v115, v72, s[24:25]
	s_add_u32 s24, s24, 0x1000
	s_addc_u32 s25, s25, 0
	global_load_dword v116, v72, s[24:25]
	s_add_u32 s24, s24, 0x1000
	s_addc_u32 s25, s25, 0
	global_load_dword v117, v72, s[24:25]
	s_add_u32 s24, s24, 0x1000
	s_addc_u32 s25, s25, 0
	global_load_dword v118, v72, s[24:25]
	s_add_u32 s24, s24, 0x1000
	s_addc_u32 s25, s25, 0
	global_load_dword v119, v72, s[24:25]
	s_add_u32 s24, s24, 0x1000
	s_addc_u32 s25, s25, 0
	global_load_dword v120, v72, s[24:25]
	s_add_u32 s24, s24, 0x1000
	s_addc_u32 s25, s25, 0
	global_load_dword v121, v72, s[24:25]
	s_add_u32 s24, s24, 0x1000
	s_addc_u32 s25, s25, 0
	s_waitcnt lgkmcnt(15)
	v_pk_fma_f32 v[2:3], v[122:123], v[8:9], v[2:3] op_sel_hi:[0,1,1]
	v_pk_fma_f32 v[4:5], v[122:123], v[10:11], v[4:5] op_sel_hi:[0,1,1]
	s_waitcnt lgkmcnt(14)
	v_pk_fma_f32 v[2:3], v[122:123], v[12:13], v[2:3] op_sel:[1,0,0] op_sel_hi:[1,1,1]
	v_pk_fma_f32 v[4:5], v[122:123], v[14:15], v[4:5] op_sel:[1,0,0] op_sel_hi:[1,1,1]
	s_waitcnt lgkmcnt(13)
	v_pk_fma_f32 v[2:3], v[124:125], v[16:17], v[2:3] op_sel_hi:[0,1,1]
	v_pk_fma_f32 v[4:5], v[124:125], v[18:19], v[4:5] op_sel_hi:[0,1,1]
	s_waitcnt lgkmcnt(12)
	v_pk_fma_f32 v[2:3], v[124:125], v[20:21], v[2:3] op_sel:[1,0,0] op_sel_hi:[1,1,1]
	v_pk_fma_f32 v[4:5], v[124:125], v[22:23], v[4:5] op_sel:[1,0,0] op_sel_hi:[1,1,1]
	s_waitcnt lgkmcnt(11)
	v_pk_fma_f32 v[2:3], v[126:127], v[24:25], v[2:3] op_sel_hi:[0,1,1]
	v_pk_fma_f32 v[4:5], v[126:127], v[26:27], v[4:5] op_sel_hi:[0,1,1]
	s_waitcnt lgkmcnt(10)
	v_pk_fma_f32 v[2:3], v[126:127], v[28:29], v[2:3] op_sel:[1,0,0] op_sel_hi:[1,1,1]
	v_pk_fma_f32 v[4:5], v[126:127], v[30:31], v[4:5] op_sel:[1,0,0] op_sel_hi:[1,1,1]
	s_waitcnt lgkmcnt(9)
	v_pk_fma_f32 v[2:3], v[128:129], v[32:33], v[2:3] op_sel_hi:[0,1,1]
	v_pk_fma_f32 v[4:5], v[128:129], v[34:35], v[4:5] op_sel_hi:[0,1,1]
	s_waitcnt lgkmcnt(8)
	v_pk_fma_f32 v[2:3], v[128:129], v[36:37], v[2:3] op_sel:[1,0,0] op_sel_hi:[1,1,1]
	v_pk_fma_f32 v[4:5], v[128:129], v[38:39], v[4:5] op_sel:[1,0,0] op_sel_hi:[1,1,1]
	s_waitcnt lgkmcnt(7)
	v_pk_fma_f32 v[2:3], v[130:131], v[40:41], v[2:3] op_sel_hi:[0,1,1]
	v_pk_fma_f32 v[4:5], v[130:131], v[42:43], v[4:5] op_sel_hi:[0,1,1]
	s_waitcnt lgkmcnt(6)
; #define LAS __attribute__((address_space(3)))
; __global__ void __launch_bounds__(512, 2) hybrid_fwd(Args args) {
;     ...
;             const float* wp = w_pool_out + (size_t)g * 128 * DM + n;
; #pragma unroll 16
;             for (int d = 0; d < 128; ++d) {
;                 const float p = wp[(size_t)d * DM];
;                 const f32x4 a = *(const LAS f32x4*)(scr + d * 4);
;                 acc[0] += a[0] * p; acc[1] += a[1] * p; acc[2] += a[2] * p; acc[3] += a[3] * p;
;             }
	v_pk_fma_f32 v[2:3], v[130:131], v[44:45], v[2:3] op_sel:[1,0,0] op_sel_hi:[1,1,1]
	v_pk_fma_f32 v[4:5], v[130:131], v[46:47], v[4:5] op_sel:[1,0,0] op_sel_hi:[1,1,1]
	s_waitcnt lgkmcnt(5)
	v_pk_fma_f32 v[2:3], v[132:133], v[48:49], v[2:3] op_sel_hi:[0,1,1]
	v_pk_fma_f32 v[4:5], v[132:133], v[50:51], v[4:5] op_sel_hi:[0,1,1]
	s_waitcnt lgkmcnt(4)
	v_pk_fma_f32 v[2:3], v[132:133], v[52:53], v[2:3] op_sel:[1,0,0] op_sel_hi:[1,1,1]
	v_pk_fma_f32 v[4:5], v[132:133], v[54:55], v[4:5] op_sel:[1,0,0] op_sel_hi:[1,1,1]
	s_waitcnt lgkmcnt(3)
	v_pk_fma_f32 v[2:3], v[134:135], v[56:57], v[2:3] op_sel_hi:[0,1,1]
	v_pk_fma_f32 v[4:5], v[134:135], v[58:59], v[4:5] op_sel_hi:[0,1,1]
	s_waitcnt lgkmcnt(2)
	v_pk_fma_f32 v[2:3], v[134:135], v[60:61], v[2:3] op_sel:[1,0,0] op_sel_hi:[1,1,1]
	v_pk_fma_f32 v[4:5], v[134:135], v[62:63], v[4:5] op_sel:[1,0,0] op_sel_hi:[1,1,1]
	s_waitcnt lgkmcnt(1)
	v_pk_fma_f32 v[2:3], v[136:137], v[64:65], v[2:3] op_sel_hi:[0,1,1]
	v_pk_fma_f32 v[4:5], v[136:137], v[66:67], v[4:5] op_sel_hi:[0,1,1]
	s_waitcnt lgkmcnt(0)
	v_pk_fma_f32 v[2:3], v[136:137], v[68:69], v[2:3] op_sel:[1,0,0] op_sel_hi:[1,1,1]
	v_pk_fma_f32 v[4:5], v[136:137], v[70:71], v[4:5] op_sel:[1,0,0] op_sel_hi:[1,1,1]
	ds_read_b128 v[8:11], v73 offset:1024
	ds_read_b128 v[12:15], v73 offset:1040
	ds_read_b128 v[16:19], v73 offset:1056
	ds_read_b128 v[20:23], v73 offset:1072
	ds_read_b128 v[24:27], v73 offset:1088
	ds_read_b128 v[28:31], v73 offset:1104
	ds_read_b128 v[32:35], v73 offset:1120
	ds_read_b128 v[36:39], v73 offset:1136
	ds_read_b128 v[40:43], v73 offset:1152
	ds_read_b128 v[44:47], v73 offset:1168
	ds_read_b128 v[48:51], v73 offset:1184
	ds_read_b128 v[52:55], v73 offset:1200
	ds_read_b128 v[56:59], v73 offset:1216
	ds_read_b128 v[60:63], v73 offset:1232
	ds_read_b128 v[64:67], v73 offset:1248
	ds_read_b128 v[68:71], v73 offset:1264
	s_waitcnt vmcnt(32)
	global_load_dword v122, v72, s[24:25]
	s_add_u32 s24, s24, 0x1000
	s_addc_u32 s25, s25, 0
	global_load_dword v123, v72, s[24:25]
	s_add_u32 s24, s24, 0x1000
	s_addc_u32 s25, s25, 0
	global_load_dword v124, v72, s[24:25]
	s_add_u32 s24, s24, 0x1000
	s_addc_u32 s25, s25, 0
	global_load_dword v125, v72, s[24:25]
	s_add_u32 s24, s24, 0x1000
	s_addc_u32 s25, s25, 0
	global_load_dword v126, v72, s[24:25]
	s_add_u32 s24, s24, 0x1000
	s_addc_u32 s25, s25, 0
	global_load_dword v127, v72, s[24:25]
	s_add_u32 s24, s24, 0x1000
	s_addc_u32 s25, s25, 0
	global_load_dword v128, v72, s[24:25]
	s_add_u32 s24, s24, 0x1000
	s_addc_u32 s25, s25, 0
	global_load_dword v129, v72, s[24:25]
	s_add_u32 s24, s24, 0x1000
	s_addc_u32 s25, s25, 0
	global_load_dword v130, v72, s[24:25]
	s_add_u32 s24, s24, 0x1000
	s_addc_u32 s25, s25, 0
	global_load_dword v131, v72, s[24:25]
	s_add_u32 s24, s24, 0x1000
	s_addc_u32 s25, s25, 0
	global_load_dword v132, v72, s[24:25]
	s_add_u32 s24, s24, 0x1000
	s_addc_u32 s25, s25, 0
	global_load_dword v133, v72, s[24:25]
	s_add_u32 s24, s24, 0x1000
	s_addc_u32 s25, s25, 0
	global_load_dword v134, v72, s[24:25]
	s_add_u32 s24, s24, 0x1000
	s_addc_u32 s25, s25, 0
	global_load_dword v135, v72, s[24:25]
	s_add_u32 s24, s24, 0x1000
	s_addc_u32 s25, s25, 0
	global_load_dword v136, v72, s[24:25]
	s_add_u32 s24, s24, 0x1000
	s_addc_u32 s25, s25, 0
	global_load_dword v137, v72, s[24:25]
	s_add_u32 s24, s24, 0x1000
	s_addc_u32 s25, s25, 0
	s_waitcnt lgkmcnt(15)
	v_pk_fma_f32 v[2:3], v[74:75], v[8:9], v[2:3] op_sel_hi:[0,1,1]
	v_pk_fma_f32 v[4:5], v[74:75], v[10:11], v[4:5] op_sel_hi:[0,1,1]
	s_waitcnt lgkmcnt(14)
	v_pk_fma_f32 v[2:3], v[74:75], v[12:13], v[2:3] op_sel:[1,0,0] op_sel_hi:[1,1,1]
	v_pk_fma_f32 v[4:5], v[74:75], v[14:15], v[4:5] op_sel:[1,0,0] op_sel_hi:[1,1,1]
	s_waitcnt lgkmcnt(13)
	v_pk_fma_f32 v[2:3], v[76:77], v[16:17], v[2:3] op_sel_hi:[0,1,1]
	v_pk_fma_f32 v[4:5], v[76:77], v[18:19], v[4:5] op_sel_hi:[0,1,1]
	s_waitcnt lgkmcnt(12)
	v_pk_fma_f32 v[2:3], v[76:77], v[20:21], v[2:3] op_sel:[1,0,0] op_sel_hi:[1,1,1]
	v_pk_fma_f32 v[4:5], v[76:77], v[22:23], v[4:5] op_sel:[1,0,0] op_sel_hi:[1,1,1]
	s_waitcnt lgkmcnt(11)
	v_pk_fma_f32 v[2:3], v[78:79], v[24:25], v[2:3] op_sel_hi:[0,1,1]
	v_pk_fma_f32 v[4:5], v[78:79], v[26:27], v[4:5] op_sel_hi:[0,1,1]
	s_waitcnt lgkmcnt(10)
	v_pk_fma_f32 v[2:3], v[78:79], v[28:29], v[2:3] op_sel:[1,0,0] op_sel_hi:[1,1,1]
	v_pk_fma_f32 v[4:5], v[78:79], v[30:31], v[4:5] op_sel:[1,0,0] op_sel_hi:[1,1,1]
	s_waitcnt lgkmcnt(9)
	v_pk_fma_f32 v[2:3], v[80:81], v[32:33], v[2:3] op_sel_hi:[0,1,1]
	v_pk_fma_f32 v[4:5], v[80:81], v[34:35], v[4:5] op_sel_hi:[0,1,1]
	s_waitcnt lgkmcnt(8)
	v_pk_fma_f32 v[2:3], v[80:81], v[36:37], v[2:3] op_sel:[1,0,0] op_sel_hi:[1,1,1]
	v_pk_fma_f32 v[4:5], v[80:81], v[38:39], v[4:5] op_sel:[1,0,0] op_sel_hi:[1,1,1]
	s_waitcnt lgkmcnt(7)
	v_pk_fma_f32 v[2:3], v[82:83], v[40:41], v[2:3] op_sel_hi:[0,1,1]
	v_pk_fma_f32 v[4:5], v[82:83], v[42:43], v[4:5] op_sel_hi:[0,1,1]
	s_waitcnt lgkmcnt(6)
	v_pk_fma_f32 v[2:3], v[82:83], v[44:45], v[2:3] op_sel:[1,0,0] op_sel_hi:[1,1,1]
	v_pk_fma_f32 v[4:5], v[82:83], v[46:47], v[4:5] op_sel:[1,0,0] op_sel_hi:[1,1,1]
	s_waitcnt lgkmcnt(5)
	v_pk_fma_f32 v[2:3], v[84:85], v[48:49], v[2:3] op_sel_hi:[0,1,1]
	v_pk_fma_f32 v[4:5], v[84:85], v[50:51], v[4:5] op_sel_hi:[0,1,1]
	s_waitcnt lgkmcnt(4)
	v_pk_fma_f32 v[2:3], v[84:85], v[52:53], v[2:3] op_sel:[1,0,0] op_sel_hi:[1,1,1]
	v_pk_fma_f32 v[4:5], v[84:85], v[54:55], v[4:5] op_sel:[1,0,0] op_sel_hi:[1,1,1]
	s_waitcnt lgkmcnt(3)
	v_pk_fma_f32 v[2:3], v[86:87], v[56:57], v[2:3] op_sel_hi:[0,1,1]
	v_pk_fma_f32 v[4:5], v[86:87], v[58:59], v[4:5] op_sel_hi:[0,1,1]
	s_waitcnt lgkmcnt(2)
; #define LAS __attribute__((address_space(3)))
; __global__ void __launch_bounds__(512, 2) hybrid_fwd(Args args) {
;     ...
;             const float* wp = w_pool_out + (size_t)g * 128 * DM + n;
; #pragma unroll 16
;             for (int d = 0; d < 128; ++d) {
;                 const float p = wp[(size_t)d * DM];
;                 const f32x4 a = *(const LAS f32x4*)(scr + d * 4);
;                 acc[0] += a[0] * p; acc[1] += a[1] * p; acc[2] += a[2] * p; acc[3] += a[3] * p;
;             }
	v_pk_fma_f32 v[2:3], v[86:87], v[60:61], v[2:3] op_sel:[1,0,0] op_sel_hi:[1,1,1]
	v_pk_fma_f32 v[4:5], v[86:87], v[62:63], v[4:5] op_sel:[1,0,0] op_sel_hi:[1,1,1]
	s_waitcnt lgkmcnt(1)
	v_pk_fma_f32 v[2:3], v[88:89], v[64:65], v[2:3] op_sel_hi:[0,1,1]
	v_pk_fma_f32 v[4:5], v[88:89], v[66:67], v[4:5] op_sel_hi:[0,1,1]
	s_waitcnt lgkmcnt(0)
	v_pk_fma_f32 v[2:3], v[88:89], v[68:69], v[2:3] op_sel:[1,0,0] op_sel_hi:[1,1,1]
	v_pk_fma_f32 v[4:5], v[88:89], v[70:71], v[4:5] op_sel:[1,0,0] op_sel_hi:[1,1,1]
	ds_read_b128 v[8:11], v73 offset:1280
	ds_read_b128 v[12:15], v73 offset:1296
	ds_read_b128 v[16:19], v73 offset:1312
	ds_read_b128 v[20:23], v73 offset:1328
	ds_read_b128 v[24:27], v73 offset:1344
	ds_read_b128 v[28:31], v73 offset:1360
	ds_read_b128 v[32:35], v73 offset:1376
	ds_read_b128 v[36:39], v73 offset:1392
	ds_read_b128 v[40:43], v73 offset:1408
	ds_read_b128 v[44:47], v73 offset:1424
	ds_read_b128 v[48:51], v73 offset:1440
	ds_read_b128 v[52:55], v73 offset:1456
	ds_read_b128 v[56:59], v73 offset:1472
	ds_read_b128 v[60:63], v73 offset:1488
	ds_read_b128 v[64:67], v73 offset:1504
	ds_read_b128 v[68:71], v73 offset:1520
	s_waitcnt vmcnt(32)
	s_waitcnt lgkmcnt(15)
	v_pk_fma_f32 v[2:3], v[90:91], v[8:9], v[2:3] op_sel_hi:[0,1,1]
	v_pk_fma_f32 v[4:5], v[90:91], v[10:11], v[4:5] op_sel_hi:[0,1,1]
	s_waitcnt lgkmcnt(14)
	v_pk_fma_f32 v[2:3], v[90:91], v[12:13], v[2:3] op_sel:[1,0,0] op_sel_hi:[1,1,1]
	v_pk_fma_f32 v[4:5], v[90:91], v[14:15], v[4:5] op_sel:[1,0,0] op_sel_hi:[1,1,1]
	s_waitcnt lgkmcnt(13)
	v_pk_fma_f32 v[2:3], v[92:93], v[16:17], v[2:3] op_sel_hi:[0,1,1]
	v_pk_fma_f32 v[4:5], v[92:93], v[18:19], v[4:5] op_sel_hi:[0,1,1]
	s_waitcnt lgkmcnt(12)
	v_pk_fma_f32 v[2:3], v[92:93], v[20:21], v[2:3] op_sel:[1,0,0] op_sel_hi:[1,1,1]
	v_pk_fma_f32 v[4:5], v[92:93], v[22:23], v[4:5] op_sel:[1,0,0] op_sel_hi:[1,1,1]
	s_waitcnt lgkmcnt(11)
	v_pk_fma_f32 v[2:3], v[94:95], v[24:25], v[2:3] op_sel_hi:[0,1,1]
	v_pk_fma_f32 v[4:5], v[94:95], v[26:27], v[4:5] op_sel_hi:[0,1,1]
	s_waitcnt lgkmcnt(10)
	v_pk_fma_f32 v[2:3], v[94:95], v[28:29], v[2:3] op_sel:[1,0,0] op_sel_hi:[1,1,1]
	v_pk_fma_f32 v[4:5], v[94:95], v[30:31], v[4:5] op_sel:[1,0,0] op_sel_hi:[1,1,1]
	s_waitcnt lgkmcnt(9)
	v_pk_fma_f32 v[2:3], v[96:97], v[32:33], v[2:3] op_sel_hi:[0,1,1]
	v_pk_fma_f32 v[4:5], v[96:97], v[34:35], v[4:5] op_sel_hi:[0,1,1]
	s_waitcnt lgkmcnt(8)
	v_pk_fma_f32 v[2:3], v[96:97], v[36:37], v[2:3] op_sel:[1,0,0] op_sel_hi:[1,1,1]
	v_pk_fma_f32 v[4:5], v[96:97], v[38:39], v[4:5] op_sel:[1,0,0] op_sel_hi:[1,1,1]
	s_waitcnt lgkmcnt(7)
	v_pk_fma_f32 v[2:3], v[98:99], v[40:41], v[2:3] op_sel_hi:[0,1,1]
	v_pk_fma_f32 v[4:5], v[98:99], v[42:43], v[4:5] op_sel_hi:[0,1,1]
	s_waitcnt lgkmcnt(6)
	v_pk_fma_f32 v[2:3], v[98:99], v[44:45], v[2:3] op_sel:[1,0,0] op_sel_hi:[1,1,1]
	v_pk_fma_f32 v[4:5], v[98:99], v[46:47], v[4:5] op_sel:[1,0,0] op_sel_hi:[1,1,1]
	s_waitcnt lgkmcnt(5)
	v_pk_fma_f32 v[2:3], v[100:101], v[48:49], v[2:3] op_sel_hi:[0,1,1]
	v_pk_fma_f32 v[4:5], v[100:101], v[50:51], v[4:5] op_sel_hi:[0,1,1]
	s_waitcnt lgkmcnt(4)
	v_pk_fma_f32 v[2:3], v[100:101], v[52:53], v[2:3] op_sel:[1,0,0] op_sel_hi:[1,1,1]
	v_pk_fma_f32 v[4:5], v[100:101], v[54:55], v[4:5] op_sel:[1,0,0] op_sel_hi:[1,1,1]
	s_waitcnt lgkmcnt(3)
	v_pk_fma_f32 v[2:3], v[102:103], v[56:57], v[2:3] op_sel_hi:[0,1,1]
	v_pk_fma_f32 v[4:5], v[102:103], v[58:59], v[4:5] op_sel_hi:[0,1,1]
	s_waitcnt lgkmcnt(2)
	v_pk_fma_f32 v[2:3], v[102:103], v[60:61], v[2:3] op_sel:[1,0,0] op_sel_hi:[1,1,1]
	v_pk_fma_f32 v[4:5], v[102:103], v[62:63], v[4:5] op_sel:[1,0,0] op_sel_hi:[1,1,1]
	s_waitcnt lgkmcnt(1)
	v_pk_fma_f32 v[2:3], v[104:105], v[64:65], v[2:3] op_sel_hi:[0,1,1]
	v_pk_fma_f32 v[4:5], v[104:105], v[66:67], v[4:5] op_sel_hi:[0,1,1]
	s_waitcnt lgkmcnt(0)
	v_pk_fma_f32 v[2:3], v[104:105], v[68:69], v[2:3] op_sel:[1,0,0] op_sel_hi:[1,1,1]
	v_pk_fma_f32 v[4:5], v[104:105], v[70:71], v[4:5] op_sel:[1,0,0] op_sel_hi:[1,1,1]
	ds_read_b128 v[8:11], v73 offset:1536
	ds_read_b128 v[12:15], v73 offset:1552
	ds_read_b128 v[16:19], v73 offset:1568
	ds_read_b128 v[20:23], v73 offset:1584
	ds_read_b128 v[24:27], v73 offset:1600
	ds_read_b128 v[28:31], v73 offset:1616
	ds_read_b128 v[32:35], v73 offset:1632
	ds_read_b128 v[36:39], v73 offset:1648
	ds_read_b128 v[40:43], v73 offset:1664
	ds_read_b128 v[44:47], v73 offset:1680
	ds_read_b128 v[48:51], v73 offset:1696
	ds_read_b128 v[52:55], v73 offset:1712
	ds_read_b128 v[56:59], v73 offset:1728
	ds_read_b128 v[60:63], v73 offset:1744
	ds_read_b128 v[64:67], v73 offset:1760
	ds_read_b128 v[68:71], v73 offset:1776
	s_waitcnt vmcnt(16)
	s_waitcnt lgkmcnt(15)
	v_pk_fma_f32 v[2:3], v[106:107], v[8:9], v[2:3] op_sel_hi:[0,1,1]
	v_pk_fma_f32 v[4:5], v[106:107], v[10:11], v[4:5] op_sel_hi:[0,1,1]
	s_waitcnt lgkmcnt(14)
	v_pk_fma_f32 v[2:3], v[106:107], v[12:13], v[2:3] op_sel:[1,0,0] op_sel_hi:[1,1,1]
	v_pk_fma_f32 v[4:5], v[106:107], v[14:15], v[4:5] op_sel:[1,0,0] op_sel_hi:[1,1,1]
	s_waitcnt lgkmcnt(13)
	v_pk_fma_f32 v[2:3], v[108:109], v[16:17], v[2:3] op_sel_hi:[0,1,1]
	v_pk_fma_f32 v[4:5], v[108:109], v[18:19], v[4:5] op_sel_hi:[0,1,1]
	s_waitcnt lgkmcnt(12)
	v_pk_fma_f32 v[2:3], v[108:109], v[20:21], v[2:3] op_sel:[1,0,0] op_sel_hi:[1,1,1]
	v_pk_fma_f32 v[4:5], v[108:109], v[22:23], v[4:5] op_sel:[1,0,0] op_sel_hi:[1,1,1]
	s_waitcnt lgkmcnt(11)
	v_pk_fma_f32 v[2:3], v[110:111], v[24:25], v[2:3] op_sel_hi:[0,1,1]
	v_pk_fma_f32 v[4:5], v[110:111], v[26:27], v[4:5] op_sel_hi:[0,1,1]
	s_waitcnt lgkmcnt(10)
	v_pk_fma_f32 v[2:3], v[110:111], v[28:29], v[2:3] op_sel:[1,0,0] op_sel_hi:[1,1,1]
	v_pk_fma_f32 v[4:5], v[110:111], v[30:31], v[4:5] op_sel:[1,0,0] op_sel_hi:[1,1,1]
	s_waitcnt lgkmcnt(9)
; #define LAS __attribute__((address_space(3)))
; __device__ __forceinline__ unsigned pk2(float lo, float hi) { return f2bf(lo) | (f2bf(hi) << 16); }
; __global__ void __launch_bounds__(512, 2) hybrid_fwd(Args args) {
;     ...
;             const float* wp = w_pool_out + (size_t)g * 128 * DM + n;
; #pragma unroll 16
;             for (int d = 0; d < 128; ++d) {
;                 const float p = wp[(size_t)d * DM];
;                 const f32x4 a = *(const LAS f32x4*)(scr + d * 4);
;                 acc[0] += a[0] * p; acc[1] += a[1] * p; acc[2] += a[2] * p; acc[3] += a[3] * p;
;             }
;             v2u o; o.x = pk2(acc[0], acc[1]); o.y = pk2(acc[2], acc[3]);
;             *(v2u*)(WC + (size_t)n * AW + g * 128 + c0) = o;
;             asm volatile("s_waitcnt lgkmcnt(0)" ::: "memory");
;         }
	v_pk_fma_f32 v[2:3], v[112:113], v[32:33], v[2:3] op_sel_hi:[0,1,1]
	v_pk_fma_f32 v[4:5], v[112:113], v[34:35], v[4:5] op_sel_hi:[0,1,1]
	s_waitcnt lgkmcnt(8)
	v_pk_fma_f32 v[2:3], v[112:113], v[36:37], v[2:3] op_sel:[1,0,0] op_sel_hi:[1,1,1]
	v_pk_fma_f32 v[4:5], v[112:113], v[38:39], v[4:5] op_sel:[1,0,0] op_sel_hi:[1,1,1]
	s_waitcnt lgkmcnt(7)
	v_pk_fma_f32 v[2:3], v[114:115], v[40:41], v[2:3] op_sel_hi:[0,1,1]
	v_pk_fma_f32 v[4:5], v[114:115], v[42:43], v[4:5] op_sel_hi:[0,1,1]
	s_waitcnt lgkmcnt(6)
	v_pk_fma_f32 v[2:3], v[114:115], v[44:45], v[2:3] op_sel:[1,0,0] op_sel_hi:[1,1,1]
	v_pk_fma_f32 v[4:5], v[114:115], v[46:47], v[4:5] op_sel:[1,0,0] op_sel_hi:[1,1,1]
	s_waitcnt lgkmcnt(5)
	v_pk_fma_f32 v[2:3], v[116:117], v[48:49], v[2:3] op_sel_hi:[0,1,1]
	v_pk_fma_f32 v[4:5], v[116:117], v[50:51], v[4:5] op_sel_hi:[0,1,1]
	s_waitcnt lgkmcnt(4)
	v_pk_fma_f32 v[2:3], v[116:117], v[52:53], v[2:3] op_sel:[1,0,0] op_sel_hi:[1,1,1]
	v_pk_fma_f32 v[4:5], v[116:117], v[54:55], v[4:5] op_sel:[1,0,0] op_sel_hi:[1,1,1]
	s_waitcnt lgkmcnt(3)
	v_pk_fma_f32 v[2:3], v[118:119], v[56:57], v[2:3] op_sel_hi:[0,1,1]
	v_pk_fma_f32 v[4:5], v[118:119], v[58:59], v[4:5] op_sel_hi:[0,1,1]
	s_waitcnt lgkmcnt(2)
	v_pk_fma_f32 v[2:3], v[118:119], v[60:61], v[2:3] op_sel:[1,0,0] op_sel_hi:[1,1,1]
	v_pk_fma_f32 v[4:5], v[118:119], v[62:63], v[4:5] op_sel:[1,0,0] op_sel_hi:[1,1,1]
	s_waitcnt lgkmcnt(1)
	v_pk_fma_f32 v[2:3], v[120:121], v[64:65], v[2:3] op_sel_hi:[0,1,1]
	v_pk_fma_f32 v[4:5], v[120:121], v[66:67], v[4:5] op_sel_hi:[0,1,1]
	s_waitcnt lgkmcnt(0)
	v_pk_fma_f32 v[2:3], v[120:121], v[68:69], v[2:3] op_sel:[1,0,0] op_sel_hi:[1,1,1]
	v_pk_fma_f32 v[4:5], v[120:121], v[70:71], v[4:5] op_sel:[1,0,0] op_sel_hi:[1,1,1]
	ds_read_b128 v[8:11], v73 offset:1792
	ds_read_b128 v[12:15], v73 offset:1808
	ds_read_b128 v[16:19], v73 offset:1824
	ds_read_b128 v[20:23], v73 offset:1840
	ds_read_b128 v[24:27], v73 offset:1856
	ds_read_b128 v[28:31], v73 offset:1872
	ds_read_b128 v[32:35], v73 offset:1888
	ds_read_b128 v[36:39], v73 offset:1904
	ds_read_b128 v[40:43], v73 offset:1920
	ds_read_b128 v[44:47], v73 offset:1936
	ds_read_b128 v[48:51], v73 offset:1952
	ds_read_b128 v[52:55], v73 offset:1968
	ds_read_b128 v[56:59], v73 offset:1984
	ds_read_b128 v[60:63], v73 offset:2000
	ds_read_b128 v[64:67], v73 offset:2016
	ds_read_b128 v[68:71], v73 offset:2032
	s_waitcnt vmcnt(0)
	s_waitcnt lgkmcnt(15)
	v_pk_fma_f32 v[2:3], v[122:123], v[8:9], v[2:3] op_sel_hi:[0,1,1]
	v_pk_fma_f32 v[4:5], v[122:123], v[10:11], v[4:5] op_sel_hi:[0,1,1]
	s_waitcnt lgkmcnt(14)
	v_pk_fma_f32 v[2:3], v[122:123], v[12:13], v[2:3] op_sel:[1,0,0] op_sel_hi:[1,1,1]
	v_pk_fma_f32 v[4:5], v[122:123], v[14:15], v[4:5] op_sel:[1,0,0] op_sel_hi:[1,1,1]
	s_waitcnt lgkmcnt(13)
	v_pk_fma_f32 v[2:3], v[124:125], v[16:17], v[2:3] op_sel_hi:[0,1,1]
	v_pk_fma_f32 v[4:5], v[124:125], v[18:19], v[4:5] op_sel_hi:[0,1,1]
	s_waitcnt lgkmcnt(12)
	v_pk_fma_f32 v[2:3], v[124:125], v[20:21], v[2:3] op_sel:[1,0,0] op_sel_hi:[1,1,1]
	v_pk_fma_f32 v[4:5], v[124:125], v[22:23], v[4:5] op_sel:[1,0,0] op_sel_hi:[1,1,1]
	s_waitcnt lgkmcnt(11)
	v_pk_fma_f32 v[2:3], v[126:127], v[24:25], v[2:3] op_sel_hi:[0,1,1]
	v_pk_fma_f32 v[4:5], v[126:127], v[26:27], v[4:5] op_sel_hi:[0,1,1]
	s_waitcnt lgkmcnt(10)
	v_pk_fma_f32 v[2:3], v[126:127], v[28:29], v[2:3] op_sel:[1,0,0] op_sel_hi:[1,1,1]
	v_pk_fma_f32 v[4:5], v[126:127], v[30:31], v[4:5] op_sel:[1,0,0] op_sel_hi:[1,1,1]
	s_waitcnt lgkmcnt(9)
	v_pk_fma_f32 v[2:3], v[128:129], v[32:33], v[2:3] op_sel_hi:[0,1,1]
	v_pk_fma_f32 v[4:5], v[128:129], v[34:35], v[4:5] op_sel_hi:[0,1,1]
	s_waitcnt lgkmcnt(8)
	v_pk_fma_f32 v[2:3], v[128:129], v[36:37], v[2:3] op_sel:[1,0,0] op_sel_hi:[1,1,1]
	v_pk_fma_f32 v[4:5], v[128:129], v[38:39], v[4:5] op_sel:[1,0,0] op_sel_hi:[1,1,1]
	s_waitcnt lgkmcnt(7)
	v_pk_fma_f32 v[2:3], v[130:131], v[40:41], v[2:3] op_sel_hi:[0,1,1]
	v_pk_fma_f32 v[4:5], v[130:131], v[42:43], v[4:5] op_sel_hi:[0,1,1]
	s_waitcnt lgkmcnt(6)
	v_pk_fma_f32 v[2:3], v[130:131], v[44:45], v[2:3] op_sel:[1,0,0] op_sel_hi:[1,1,1]
	v_pk_fma_f32 v[4:5], v[130:131], v[46:47], v[4:5] op_sel:[1,0,0] op_sel_hi:[1,1,1]
	s_waitcnt lgkmcnt(5)
	v_pk_fma_f32 v[2:3], v[132:133], v[48:49], v[2:3] op_sel_hi:[0,1,1]
	v_pk_fma_f32 v[4:5], v[132:133], v[50:51], v[4:5] op_sel_hi:[0,1,1]
	s_waitcnt lgkmcnt(4)
	v_pk_fma_f32 v[2:3], v[132:133], v[52:53], v[2:3] op_sel:[1,0,0] op_sel_hi:[1,1,1]
	v_pk_fma_f32 v[4:5], v[132:133], v[54:55], v[4:5] op_sel:[1,0,0] op_sel_hi:[1,1,1]
	s_waitcnt lgkmcnt(3)
	v_pk_fma_f32 v[2:3], v[134:135], v[56:57], v[2:3] op_sel_hi:[0,1,1]
	v_pk_fma_f32 v[4:5], v[134:135], v[58:59], v[4:5] op_sel_hi:[0,1,1]
	s_waitcnt lgkmcnt(2)
	v_pk_fma_f32 v[2:3], v[134:135], v[60:61], v[2:3] op_sel:[1,0,0] op_sel_hi:[1,1,1]
	v_pk_fma_f32 v[4:5], v[134:135], v[62:63], v[4:5] op_sel:[1,0,0] op_sel_hi:[1,1,1]
	s_waitcnt lgkmcnt(1)
	v_pk_fma_f32 v[2:3], v[136:137], v[64:65], v[2:3] op_sel_hi:[0,1,1]
	v_pk_fma_f32 v[4:5], v[136:137], v[66:67], v[4:5] op_sel_hi:[0,1,1]
	s_waitcnt lgkmcnt(0)
	v_pk_fma_f32 v[2:3], v[136:137], v[68:69], v[2:3] op_sel:[1,0,0] op_sel_hi:[1,1,1]
	v_pk_fma_f32 v[4:5], v[136:137], v[70:71], v[4:5] op_sel:[1,0,0] op_sel_hi:[1,1,1]
	v_mov_b32_e32 v72, v3
	v_mov_b32_e32 v3, v4
	v_mov_b32_e32 v4, v72
	s_lshl_b32 s7, s21, 6
	s_and_b32 s7, s7, 0x3c0
	v_add_u32_e32 v0, s7, v160
	v_ashrrev_i32_e32 v1, 31, v0
	v_and_b32_sdwa v8, v3, v7 dst_sel:DWORD dst_unused:UNUSED_PAD src0_sel:WORD_1 src1_sel:DWORD
	v_and_b32_sdwa v9, v2, v7 dst_sel:DWORD dst_unused:UNUSED_PAD src0_sel:WORD_1 src1_sel:DWORD
	v_add3_u32 v2, v2, v9, s20
	v_add3_u32 v3, v3, v8, s20
	v_and_b32_sdwa v8, v5, v7 dst_sel:DWORD dst_unused:UNUSED_PAD src0_sel:WORD_1 src1_sel:DWORD
	v_and_b32_sdwa v9, v4, v7 dst_sel:DWORD dst_unused:UNUSED_PAD src0_sel:WORD_1 src1_sel:DWORD
	v_lshlrev_b64 v[0:1], 10, v[0:1]
	v_add3_u32 v5, v5, v8, s20
	v_add3_u32 v4, v4, v9, s20
	v_lshl_add_u64 v[0:1], s[0:1], 0, v[0:1]
	s_ashr_i32 s7, s6, 31
	v_and_b32_e32 v5, 0xffff0000, v5
	v_and_b32_e32 v4, 0xffff0000, v4
	v_lshl_add_u64 v[0:1], s[6:7], 1, v[0:1]
	s_lshl_b32 s4, s4, 1
	v_or_b32_sdwa v3, v3, v5 dst_sel:DWORD dst_unused:UNUSED_PAD src0_sel:WORD_1 src1_sel:DWORD
	v_or_b32_sdwa v2, v2, v4 dst_sel:DWORD dst_unused:UNUSED_PAD src0_sel:WORD_1 src1_sel:DWORD
	v_lshl_add_u64 v[0:1], v[0:1], 0, s[4:5]
	global_store_dwordx2 v[0:1], v[2:3], off
	s_waitcnt lgkmcnt(0)
	s_add_i32 s21, s21, s90
	s_add_i32 s10, s10, s11
	s_cmpk_gt_i32 s21, 0x7ff
	s_cbranch_scc0 .LBB0_48
